# v25 + first row of each wave in the post-mixer norm: eight fp16 residual segments requested together (same edit as the row loop)
# speedup vs baseline: 1.0069x; 1.0040x over previous
; __device__ __forceinline__ f32x4 ldx(const _Float16* p) { const h16x4 h = *(const h16x4*)p; return __builtin_convertvector(h, f32x4); }
; __device__ __forceinline__ f32x4 bf4(const u32x2 w) { return (f32x4){__uint_as_float(w[0] << 16), __uint_as_float(w[0] & 0xffff0000u), __uint_as_float(w[1] << 16), __uint_as_float(w[1] & 0xffff0000u)}; }
; __device__ __forceinline__ void phase_postmix(const Params& p, const Ctx& c, int l, bool last) {
;     ...
;   auto load = [&](int row, f32x4 (&m)[8], f32x4 (&x)[8]) { const int b = row / TPB, t = row % TPB;
;     const u32x2* mr = (const u32x2*)(MIX + (size_t)row * DM); const _Float16* xr = X + (size_t)row * DM; const f32x4* xs = (const f32x4*)xrow_src(p, 0, b, t, row);
;     if (t < CTXL) { const u32x2* sl = (const u32x2*)(p.ws + OFF_Z2) + ((size_t)b * CTXL + t) * (DM / 4);
; #pragma unroll
;       for (int i = 0; i < 8; ++i) { m[i] = (f32x4){0.f, 0.f, 0.f, 0.f}; x[i] = xs[c.lane + 64 * i]; }
;       for (int s = 0; s < 8; ++s) {
; #pragma unroll
;         for (int i = 0; i < 8; ++i) m[i] += bf4(sl[(size_t)s * NB * CTXL * (DM / 4) + c.lane + 64 * i]); } }
;     else {
; #pragma unroll
;       for (int i = 0; i < 8; ++i) { m[i] = bf4(mr[c.lane + 64 * i]); x[i] = (l == 0) ? xs[c.lane + 64 * i] : ldx(xr + (c.lane + 64 * i) * 4); } } };
;     ...
;   int row = c.gwave; while (row < TT && !valid(row)) row += c.nwave;
;   if (row >= TT) return;
;   f32x4 mA[8], xA[8], mB[8], xB[8]; load(row, mA, xA);
.LBB0_978:
	s_or_b64 exec, exec, s[14:15]
	v_readlane_b32 s0, v250, 8
	v_cmp_gt_i32_e32 vcc, s38, v78
	s_mul_i32 s30, s0, 5
	s_and_saveexec_b64 s[14:15], vcc
	s_cbranch_execz .LBB0_1063
	v_mul_hi_i32 v2, v78, s94
	v_lshrrev_b32_e32 v3, 31, v2
	v_ashrrev_i32_e32 v2, 11, v2
	v_add_u32_e32 v40, v2, v3
	v_mul_i32_i24_e32 v2, 0x1100, v40
	v_sub_u32_e32 v42, v78, v2
	v_cmp_gt_i32_e32 vcc, s93, v42
	v_mov_b32_e32 v3, v0
	v_and_b32_e32 v80, 63, v1
	v_cndmask_b32_e64 v2, 0, 16, vcc
	v_lshl_add_u64 v[2:3], s[84:85], 0, v[2:3]
	global_load_dwordx2 v[2:3], v[2:3], off
	v_add_u32_e32 v1, 0xffffff00, v42
	v_ashrrev_i32_e32 v43, 31, v42
	v_cndmask_b32_e32 v5, 0, v43, vcc
	v_cndmask_b32_e32 v4, v1, v42, vcc
	v_ashrrev_i32_e32 v41, 31, v40
	v_cndmask_b32_e64 v1, 23, 19, vcc
	v_lshlrev_b64 v[4:5], 13, v[4:5]
	s_waitcnt lgkmcnt(0)
	s_add_u32 s54, s12, 0x114d0000
	v_lshlrev_b64 v[6:7], v1, v[40:41]
	s_addc_u32 s55, s13, 0
	v_cmp_lt_i32_e64 s[10:11], s27, v42
	v_lshlrev_b32_e32 v34, 3, v80
	s_waitcnt vmcnt(0)
	v_lshl_add_u64 v[2:3], v[2:3], 0, v[4:5]
	v_lshl_add_u64 v[38:39], v[6:7], 2, v[2:3]
	s_and_saveexec_b64 s[0:1], s[10:11]
	s_xor_b64 s[10:11], exec, s[0:1]
	s_cbranch_execz .LBB0_1013
	v_ashrrev_i32_e32 v79, 31, v78
	v_lshlrev_b64 v[2:3], 12, v[78:79]
	v_lshl_add_u64 v[4:5], s[54:55], 0, v[2:3]
	v_mov_b32_e32 v35, v0
	v_lshl_add_u64 v[30:31], v[4:5], 0, v[34:35]
	global_load_dwordx2 v[36:37], v[30:31], off
	v_readlane_b32 s0, v250, 14
	v_readlane_b32 s1, v250, 15
	v_lshl_add_u64 v[42:43], s[12:13], 0, v[2:3]
	s_mov_b64 s[56:57], -1
	s_and_b64 vcc, exec, s[0:1]
	s_cbranch_vccz .LBB0_982
	v_mov_b32_e32 v35, v0
	v_lshl_add_u64 v[2:3], v[42:43], 0, v[34:35]
	global_load_dwordx2 v[4:5], v[2:3], off
	global_load_dwordx2 v[8:9], v[2:3], off offset:512
	global_load_dwordx2 v[12:13], v[2:3], off offset:1024
	global_load_dwordx2 v[16:17], v[2:3], off offset:1536
	global_load_dwordx2 v[20:21], v[2:3], off offset:2048
	global_load_dwordx2 v[24:25], v[2:3], off offset:2560
	global_load_dwordx2 v[28:29], v[2:3], off offset:3072
	global_load_dwordx2 v[32:33], v[2:3], off offset:3584
	s_mov_b64 s[56:57], 0
	s_waitcnt vmcnt(7)
	v_cvt_f32_f16_e32 v2, v4
	v_cvt_f32_f16_sdwa v3, v4 dst_sel:DWORD dst_unused:UNUSED_PAD src0_sel:WORD_1
	v_cvt_f32_f16_e32 v4, v5
	v_cvt_f32_f16_sdwa v5, v5 dst_sel:DWORD dst_unused:UNUSED_PAD src0_sel:WORD_1

; __device__ __forceinline__ f32x4 ldx(const _Float16* p) { const h16x4 h = *(const h16x4*)p; return __builtin_convertvector(h, f32x4); }
; __device__ __forceinline__ f32x4 bf4(const u32x2 w) { return (f32x4){__uint_as_float(w[0] << 16), __uint_as_float(w[0] & 0xffff0000u), __uint_as_float(w[1] << 16), __uint_as_float(w[1] & 0xffff0000u)}; }
; __device__ __forceinline__ void phase_postmix(const Params& p, const Ctx& c, int l, bool last) {
;     ...
; #pragma unroll
;       for (int i = 0; i < 8; ++i) { m[i] = bf4(mr[c.lane + 64 * i]); x[i] = (l == 0) ? xs[c.lane + 64 * i] : ldx(xr + (c.lane + 64 * i) * 4); } } };
.LBB0_984:
	s_nop 0
	global_load_dwordx2 v[40:41], v[30:31], off offset:512
	s_and_b64 vcc, exec, s[0:1]
	s_mov_b64 s[56:57], -1
	s_cbranch_vccnz .LBB0_986
	s_waitcnt vmcnt(7)
	v_cvt_f32_f16_e32 v6, v8
	v_cvt_f32_f16_sdwa v7, v8 dst_sel:DWORD dst_unused:UNUSED_PAD src0_sel:WORD_1
	v_cvt_f32_f16_e32 v8, v9
	v_cvt_f32_f16_sdwa v9, v9 dst_sel:DWORD dst_unused:UNUSED_PAD src0_sel:WORD_1
	s_cbranch_execnz .LBB0_988
	s_branch .LBB0_987

; __device__ __forceinline__ f32x4 ldx(const _Float16* p) { const h16x4 h = *(const h16x4*)p; return __builtin_convertvector(h, f32x4); }
; __device__ __forceinline__ f32x4 bf4(const u32x2 w) { return (f32x4){__uint_as_float(w[0] << 16), __uint_as_float(w[0] & 0xffff0000u), __uint_as_float(w[1] << 16), __uint_as_float(w[1] & 0xffff0000u)}; }
; __device__ __forceinline__ void phase_postmix(const Params& p, const Ctx& c, int l, bool last) {
;     ...
; #pragma unroll
;       for (int i = 0; i < 8; ++i) { m[i] = bf4(mr[c.lane + 64 * i]); x[i] = (l == 0) ? xs[c.lane + 64 * i] : ldx(xr + (c.lane + 64 * i) * 4); } } };
.LBB0_988:
	s_nop 0
	global_load_dwordx2 v[44:45], v[30:31], off offset:1024
	s_and_b64 vcc, exec, s[0:1]
	s_mov_b64 s[56:57], -1
	s_cbranch_vccnz .LBB0_990
	s_waitcnt vmcnt(7)
	v_cvt_f32_f16_e32 v10, v12
	v_cvt_f32_f16_sdwa v11, v12 dst_sel:DWORD dst_unused:UNUSED_PAD src0_sel:WORD_1
	v_cvt_f32_f16_e32 v12, v13
	v_cvt_f32_f16_sdwa v13, v13 dst_sel:DWORD dst_unused:UNUSED_PAD src0_sel:WORD_1
	s_cbranch_execnz .LBB0_992
	s_branch .LBB0_991

; __device__ __forceinline__ f32x4 ldx(const _Float16* p) { const h16x4 h = *(const h16x4*)p; return __builtin_convertvector(h, f32x4); }
; __device__ __forceinline__ f32x4 bf4(const u32x2 w) { return (f32x4){__uint_as_float(w[0] << 16), __uint_as_float(w[0] & 0xffff0000u), __uint_as_float(w[1] << 16), __uint_as_float(w[1] & 0xffff0000u)}; }
; __device__ __forceinline__ void phase_postmix(const Params& p, const Ctx& c, int l, bool last) {
;     ...
; #pragma unroll
;       for (int i = 0; i < 8; ++i) { m[i] = bf4(mr[c.lane + 64 * i]); x[i] = (l == 0) ? xs[c.lane + 64 * i] : ldx(xr + (c.lane + 64 * i) * 4); } } };
.LBB0_992:
	s_nop 0
	global_load_dwordx2 v[46:47], v[30:31], off offset:1536
	s_and_b64 vcc, exec, s[0:1]
	s_mov_b64 s[56:57], -1
	s_cbranch_vccnz .LBB0_994
	s_waitcnt vmcnt(7)
	v_cvt_f32_f16_e32 v14, v16
	v_cvt_f32_f16_sdwa v15, v16 dst_sel:DWORD dst_unused:UNUSED_PAD src0_sel:WORD_1
	v_cvt_f32_f16_e32 v16, v17
	v_cvt_f32_f16_sdwa v17, v17 dst_sel:DWORD dst_unused:UNUSED_PAD src0_sel:WORD_1
	s_cbranch_execnz .LBB0_996
	s_branch .LBB0_995

; __device__ __forceinline__ f32x4 ldx(const _Float16* p) { const h16x4 h = *(const h16x4*)p; return __builtin_convertvector(h, f32x4); }
; __device__ __forceinline__ f32x4 bf4(const u32x2 w) { return (f32x4){__uint_as_float(w[0] << 16), __uint_as_float(w[0] & 0xffff0000u), __uint_as_float(w[1] << 16), __uint_as_float(w[1] & 0xffff0000u)}; }
; __device__ __forceinline__ void phase_postmix(const Params& p, const Ctx& c, int l, bool last) {
;     ...
; #pragma unroll
;       for (int i = 0; i < 8; ++i) { m[i] = bf4(mr[c.lane + 64 * i]); x[i] = (l == 0) ? xs[c.lane + 64 * i] : ldx(xr + (c.lane + 64 * i) * 4); } } };
.LBB0_996:
	s_nop 0
	global_load_dwordx2 v[48:49], v[30:31], off offset:2048
	s_and_b64 vcc, exec, s[0:1]
	s_mov_b64 s[56:57], -1
	s_cbranch_vccnz .LBB0_998
	s_waitcnt vmcnt(7)
	v_cvt_f32_f16_e32 v18, v20
	v_cvt_f32_f16_sdwa v19, v20 dst_sel:DWORD dst_unused:UNUSED_PAD src0_sel:WORD_1
	v_cvt_f32_f16_e32 v20, v21
	v_cvt_f32_f16_sdwa v21, v21 dst_sel:DWORD dst_unused:UNUSED_PAD src0_sel:WORD_1
	s_cbranch_execnz .LBB0_1000
	s_branch .LBB0_999

; __device__ __forceinline__ f32x4 ldx(const _Float16* p) { const h16x4 h = *(const h16x4*)p; return __builtin_convertvector(h, f32x4); }
; __device__ __forceinline__ f32x4 bf4(const u32x2 w) { return (f32x4){__uint_as_float(w[0] << 16), __uint_as_float(w[0] & 0xffff0000u), __uint_as_float(w[1] << 16), __uint_as_float(w[1] & 0xffff0000u)}; }
; __device__ __forceinline__ void phase_postmix(const Params& p, const Ctx& c, int l, bool last) {
;     ...
; #pragma unroll
;       for (int i = 0; i < 8; ++i) { m[i] = bf4(mr[c.lane + 64 * i]); x[i] = (l == 0) ? xs[c.lane + 64 * i] : ldx(xr + (c.lane + 64 * i) * 4); } } };
.LBB0_1000:
	s_nop 0
	global_load_dwordx2 v[50:51], v[30:31], off offset:2560
	s_and_b64 vcc, exec, s[0:1]
	s_mov_b64 s[56:57], -1
	s_cbranch_vccnz .LBB0_1002
	s_waitcnt vmcnt(7)
	v_cvt_f32_f16_e32 v22, v24
	v_cvt_f32_f16_sdwa v23, v24 dst_sel:DWORD dst_unused:UNUSED_PAD src0_sel:WORD_1
	v_cvt_f32_f16_e32 v24, v25
	v_cvt_f32_f16_sdwa v25, v25 dst_sel:DWORD dst_unused:UNUSED_PAD src0_sel:WORD_1
	s_cbranch_execnz .LBB0_1004
	s_branch .LBB0_1003

; __device__ __forceinline__ f32x4 ldx(const _Float16* p) { const h16x4 h = *(const h16x4*)p; return __builtin_convertvector(h, f32x4); }
; __device__ __forceinline__ f32x4 bf4(const u32x2 w) { return (f32x4){__uint_as_float(w[0] << 16), __uint_as_float(w[0] & 0xffff0000u), __uint_as_float(w[1] << 16), __uint_as_float(w[1] & 0xffff0000u)}; }
; __device__ __forceinline__ void phase_postmix(const Params& p, const Ctx& c, int l, bool last) {
;     ...
; #pragma unroll
;       for (int i = 0; i < 8; ++i) { m[i] = bf4(mr[c.lane + 64 * i]); x[i] = (l == 0) ? xs[c.lane + 64 * i] : ldx(xr + (c.lane + 64 * i) * 4); } } };
.LBB0_1004:
	s_nop 0
	global_load_dwordx2 v[52:53], v[30:31], off offset:3072
	s_and_b64 vcc, exec, s[0:1]
	s_mov_b64 s[56:57], -1
	s_cbranch_vccnz .LBB0_1006
	s_waitcnt vmcnt(7)
	v_cvt_f32_f16_e32 v26, v28
	v_cvt_f32_f16_sdwa v27, v28 dst_sel:DWORD dst_unused:UNUSED_PAD src0_sel:WORD_1
	v_cvt_f32_f16_e32 v28, v29
	v_cvt_f32_f16_sdwa v29, v29 dst_sel:DWORD dst_unused:UNUSED_PAD src0_sel:WORD_1
	s_cbranch_execnz .LBB0_1008
	s_branch .LBB0_1007

; __device__ __forceinline__ f32x4 ldx(const _Float16* p) { const h16x4 h = *(const h16x4*)p; return __builtin_convertvector(h, f32x4); }
; __device__ __forceinline__ f32x4 bf4(const u32x2 w) { return (f32x4){__uint_as_float(w[0] << 16), __uint_as_float(w[0] & 0xffff0000u), __uint_as_float(w[1] << 16), __uint_as_float(w[1] & 0xffff0000u)}; }
; __device__ __forceinline__ void phase_postmix(const Params& p, const Ctx& c, int l, bool last) {
;     ...
; #pragma unroll
;       for (int i = 0; i < 8; ++i) { m[i] = bf4(mr[c.lane + 64 * i]); x[i] = (l == 0) ? xs[c.lane + 64 * i] : ldx(xr + (c.lane + 64 * i) * 4); } } };
.LBB0_1008:
	s_nop 0
	global_load_dwordx2 v[54:55], v[30:31], off offset:3584
	s_and_b64 vcc, exec, s[0:1]
	s_mov_b64 s[56:57], -1
	s_cbranch_vccnz .LBB0_1010
	s_waitcnt vmcnt(7)
	v_cvt_f32_f16_e32 v30, v32
	v_cvt_f32_f16_sdwa v31, v32 dst_sel:DWORD dst_unused:UNUSED_PAD src0_sel:WORD_1
	v_cvt_f32_f16_e32 v32, v33
	v_cvt_f32_f16_sdwa v33, v33 dst_sel:DWORD dst_unused:UNUSED_PAD src0_sel:WORD_1
	s_cbranch_execz .LBB0_1011
	s_branch .LBB0_1012
